# next tiles' DMA pieces issued in the first MFMA gaps of the step (they must land before the closing barrier); K pieces after the fourth score MFMA
# speedup vs baseline: 1.0085x; 1.0061x over previous
; #define SBAR() __builtin_amdgcn_sched_barrier(0)
; #define KDMA(k0, b) do { const char* g_ = (const char*)(Kh + (long)(k0) * DM); char* l_ = K_lds + (b) * 16384 + wu * 1024; \
;     DMA16(g_ + koff[0], l_); DMA16(g_ + koff[1], l_ + 8192); } while (0)
; #define VDMA(k0, b) do { const char* g_ = (const char*)(Vh + (long)(k0) * DM); char* l_ = V_lds + (b) * 32768 + wu * 1024; \
;     DMA16(g_ + voff[0], l_); DMA16(g_ + voff[1], l_ + 8192); DMA16(g_ + voff[0] + 256, l_ + 16384); DMA16(g_ + voff[1] + 256, l_ + 16384 + 8192); } while (0)
; #define LWAIT() do { asm volatile("s_waitcnt lgkmcnt(0)" ::: "memory"); SBAR(); } while (0)
; #define VMMP(D0, X) do { if (!(PROBE & 8)) VMM(D0, X); } while (0)
; #define SMXP(c) do { if (!(PROBE & 2)) { if (more) SMX_CH(c); } } while (0)
; template <int PROBE, int MODE>
; DI void dattn_body(const u16* __restrict__ Qb, const u16* __restrict__ Kh, const u16* __restrict__ Vh, u16* __restrict__ Ob, const u16* __restrict__ O1, float lam, const float* __restrict__ subg, int seq, int q0, float kmax2, char* lds) {
;     ...
;   for (int j = 0; j < NT; ++j) {
;     const bool more = j + 1 < NT;
;     if (!(PROBE & 1)) {
;       if (j + 2 < NT) KDMA((j + 2) * KVBLK, j & 1);
;       if (more) VDMA((j + 1) * KVBLK, (j + 1) & 1);
;     }
;     bf16x8 kf[8];
;     if (more) { const char* Ks_ = K_lds + ((j + 1) & 1) * 16384;
; #pragma unroll
;       for (int d0 = 0; d0 < 8; ++d0) kf[d0] = *reinterpret_cast<const bf16x8*>(Ks_ + KSWZ(32 * kh + r32, (d0 * 16 + hi * 8) * 2)); }
;     const bf16x8 pb0 = *(const bf16x8*)(pr + (j & 1) * 16384), pb1 = *(const bf16x8*)(pr + (j & 1) * 16384 + 16);
;     const int vb = vb0 + (j & 1) * 32768;
;     s16x4 va0, va1, va2, va3, va4, va5, va6, va7, vc0, vc1, vc2, vc3, vc4, vc5, vc6, vc7;
;     VRD(0, va);
;     if (more) { asm volatile("s_waitcnt lgkmcnt(10)" ::: "memory"); SBAR();
;       if (!(PROBE & 4)) { S = f32x16{};
; #pragma unroll
;       for (int d0 = 0; d0 < 8; ++d0) S = __builtin_amdgcn_mfma_f32_32x32x16_bf16(kf[d0], qr[d0], S, 0, 0, 0); }
;       SBAR(); }
;     const bf16x8 A0 = kh ? pb0 : po0, A1 = kh ? pb1 : po1, A2 = kh ? po0 : pb0, A3 = kh ? po1 : pb1;
;     SMX_SETUP(j + 1)
;     ...
;     LWAIT(); VRD(1, vc); VMMP(0, va); SMXP(0);
;     LWAIT(); VRD(2, va); VMMP(1, vc); SMXP(1);
;     LWAIT(); VRD(3, vc); VMMP(2, va); SMXP(2);
;     LWAIT(); VMMP(3, vc); SMXP(3);
.Lfast0:
	s_sub_i32 s72, s18, 64
	s_and_b32 s101, s25, 0x4000
	s_addk_i32 s25, 0x4000
	s_and_b32 s19, s25, 0x4000
	s_and_b32 s48, s55, 1
	v_lshl_add_u32 v71, s48, 14, v210
	s_bfe_u32 s100, s85, 0x1000a
	s_lshl_b32 s100, s100, 13
	s_lshl_b32 s48, s48, 15
	s_sub_i32 s74, s48, s100
	s_add_i32 s48, s48, s100
	v_add_u32_e32 v216, s48, v212
	v_add_u32_e32 v233, s74, v212
	v_add_u32_e32 v68, s19, v213
	v_add_u32_e32 v64, v68, v198
	v_add_u32_e32 v69, v68, v199
	ds_read_b64_tr_b16 v[234:235], v216 offset:0
	ds_read_b64_tr_b16 v[236:237], v216 offset:0x800
	ds_read_b128 v[64:67], v64
	ds_read_b128 v[118:121], v69
	ds_read_b128 v[162:165], v71
	ds_read_b128 v[166:169], v71 offset:16
	v_add_u32_e32 v69, v68, v200
	v_add_u32_e32 v70, v68, v201
	ds_read_b128 v[122:125], v69
	ds_read_b128 v[126:129], v70
	ds_read_b64_tr_b16 v[238:239], v216 offset:0x1000
	ds_read_b64_tr_b16 v[240:241], v216 offset:0x1800
	v_add_u32_e32 v69, v68, v202
	v_add_u32_e32 v70, v68, v203
	ds_read_b128 v[134:137], v69
	ds_read_b128 v[138:141], v70
	v_add_u32_e32 v142, v68, v204
	v_add_u32_e32 v146, v68, v205
	s_cmp_gt_i32 s72, s87
	s_cselect_b32 s100, s21, s20
	v_sub_f32_e32 v160, s100, v158
	s_lshl_b32 s48, s72, 12
	s_add_u32 s48, s16, s48
	s_addc_u32 s49, s17, 0
	s_add_u32 s74, s48, 0x100
	s_addc_u32 s75, s49, 0
	s_and_b32 s100, s54, 0x8000
	s_add_i32 s100, s85, s100
	s_mov_b32 m0, s100
	s_waitcnt lgkmcnt(10)
	v_mfma_f32_32x32x16_bf16 v[0:15], v[114:117], v[234:237], v[0:15]
	global_load_lds_dwordx4 v176, s[48:49]
	ds_read_b64_tr_b16 v[242:243], v233 offset:0x2000
	ds_read_b64_tr_b16 v[244:245], v233 offset:0x2800
	s_add_i32 m0, s100, 0x2000
	s_waitcnt lgkmcnt(11)
	v_mfma_f32_32x32x16_bf16 v[64:79], v[64:67], v[82:85], 0
	global_load_lds_dwordx4 v156, s[48:49]
	ds_read_b128 v[142:145], v142
	ds_read_b128 v[146:149], v146
	s_add_i32 m0, s100, 0x4000
	s_waitcnt lgkmcnt(12)
	v_mfma_f32_32x32x16_bf16 v[64:79], v[118:121], v[86:89], v[64:79]
	global_load_lds_dwordx4 v176, s[74:75]
	ds_read_b64_tr_b16 v[246:247], v233 offset:0x3000
	ds_read_b64_tr_b16 v[248:249], v233 offset:0x3800
	s_add_i32 m0, s100, 0x6000
	s_waitcnt lgkmcnt(11)
	v_mfma_f32_32x32x16_bf16 v[64:79], v[122:125], v[90:93], v[64:79]
	global_load_lds_dwordx4 v156, s[74:75]
	s_waitcnt lgkmcnt(10)
	v_mfma_f32_32x32x16_bf16 v[64:79], v[126:129], v[94:97], v[64:79]
	ds_read_b64_tr_b16 v[126:127], v233 offset:0x3200
	ds_read_b64_tr_b16 v[128:129], v233 offset:0x3a00
	s_waitcnt lgkmcnt(10)
	v_mfma_f32_32x32x16_bf16 v[0:15], v[130:133], v[238:241], v[0:15]
	s_add_i32 s48, s55, 2
	s_cmp_ge_u32 s48, s11
	s_cbranch_scc1 .Lfast0_k_done
	s_lshl_b32 s48, s18, 12
	s_add_u32 s48, s14, s48
	s_addc_u32 s49, s15, 0
	s_add_i32 s100, s82, s101
	s_mov_b32 m0, s100
	s_nop 0
	global_load_lds_dwordx4 v152, s[48:49]
	s_add_i32 m0, s100, 0x2000
	s_nop 0
	global_load_lds_dwordx4 v154, s[48:49]
; #define DMAWAIT() asm volatile("s_waitcnt vmcnt(0)" ::: "memory")
; #define SMX_FIN(pbuf) do { _Pragma("unroll") for (int r = 0; r < 16; ++r) l_reg += S[r]; \
;     PK4S(0, po0); PK4S(8, po1); \
;     *(bf16x8*)(pw + (pbuf) * 16384) = po0; *(bf16x8*)(pw + (pbuf) * 16384 + 16) = po1; } while (0)
; #define VRD(D0, X) do { X##0 = tr_read<v_rd_off(D0, 0, 0)>(vb); X##1 = tr_read<v_rd_off(D0, 0, 1)>(vb); X##2 = tr_read<v_rd_off(D0, 1, 0)>(vb); X##3 = tr_read<v_rd_off(D0, 1, 1)>(vb); \
;     X##4 = tr_read<v_rd_off(D0, 2, 0)>(vb); X##5 = tr_read<v_rd_off(D0, 2, 1)>(vb); X##6 = tr_read<v_rd_off(D0, 3, 0)>(vb); X##7 = tr_read<v_rd_off(D0, 3, 1)>(vb); } while (0)
; #define LWAIT() do { asm volatile("s_waitcnt lgkmcnt(0)" ::: "memory"); SBAR(); } while (0)
; #define VMMP(D0, X) do { if (!(PROBE & 8)) VMM(D0, X); } while (0)
; #define SMXP(c) do { if (!(PROBE & 2)) { if (more) SMX_CH(c); } } while (0)
; template <int PROBE, int MODE>
; DI void dattn_body(const u16* __restrict__ Qb, const u16* __restrict__ Kh, const u16* __restrict__ Vh, u16* __restrict__ Ob, const u16* __restrict__ O1, float lam, const float* __restrict__ subg, int seq, int q0, float kmax2, char* lds) {
;     ...
;     LWAIT(); VRD(1, vc); VMMP(0, va); SMXP(0);
;     LWAIT(); VRD(2, va); VMMP(1, vc); SMXP(1);
;     LWAIT(); VRD(3, vc); VMMP(2, va); SMXP(2);
;     LWAIT(); VMMP(3, vc); SMXP(3);
;     if (!(PROBE & 2)) { if (more) SMX_FIN((j + 1) & 1); }
;     DMAWAIT();
;     __syncthreads();
.Lfast0_k_done:
	s_waitcnt lgkmcnt(9)
	v_mfma_f32_32x32x16_bf16 v[64:79], v[134:137], v[98:101], v[64:79]
	ds_read_b64_tr_b16 v[134:135], v233 offset:0x2200
	ds_read_b64_tr_b16 v[136:137], v233 offset:0x2a00
	s_waitcnt lgkmcnt(10)
	v_mfma_f32_32x32x16_bf16 v[64:79], v[138:141], v[102:105], v[64:79]
	ds_read_b64_tr_b16 v[138:139], v216 offset:0x200
	ds_read_b64_tr_b16 v[140:141], v216 offset:0xa00
	s_waitcnt lgkmcnt(10)
	v_mfma_f32_32x32x16_bf16 v[0:15], v[162:165], v[242:245], v[0:15]
	s_waitcnt lgkmcnt(9)
	v_mfma_f32_32x32x16_bf16 v[64:79], v[142:145], v[106:109], v[64:79]
	ds_read_b64_tr_b16 v[142:143], v216 offset:0x1200
	ds_read_b64_tr_b16 v[144:145], v216 offset:0x1a00
	s_waitcnt lgkmcnt(10)
	v_mfma_f32_32x32x16_bf16 v[64:79], v[146:149], v[110:113], v[64:79]
	s_waitcnt lgkmcnt(8)
	v_mfma_f32_32x32x16_bf16 v[0:15], v[166:169], v[246:249], v[0:15]
	s_waitcnt lgkmcnt(2)
	v_mfma_f32_32x32x16_bf16 v[16:31], v[114:117], v[138:141], v[16:31]
	ds_read_b64_tr_b16 v[146:147], v216 offset:0x400
	ds_read_b64_tr_b16 v[148:149], v216 offset:0xc00
	s_nop 7
	s_nop 0
	v_fma_f32 v118, v64, s12, v160
	v_fma_f32 v119, v65, s12, v160
	v_fma_f32 v120, v66, s12, v160
	v_fma_f32 v121, v67, s12, v160
	v_fma_f32 v122, v68, s12, v160
	v_fma_f32 v123, v69, s12, v160
	s_waitcnt lgkmcnt(2)
	v_mfma_f32_32x32x16_bf16 v[16:31], v[130:133], v[142:145], v[16:31]
	ds_read_b64_tr_b16 v[142:143], v216 offset:0x1400
	ds_read_b64_tr_b16 v[144:145], v216 offset:0x1c00
	v_fma_f32 v124, v70, s12, v160
	v_fma_f32 v125, v71, s12, v160
	v_exp_f32_e32 v118, v118
	v_exp_f32_e32 v119, v119
	v_exp_f32_e32 v120, v120
	v_exp_f32_e32 v121, v121
	v_fma_f32 v244, v72, s12, v160
	v_fma_f32 v245, v73, s12, v160
	v_mfma_f32_32x32x16_bf16 v[16:31], v[162:165], v[134:137], v[16:31]
	ds_read_b64_tr_b16 v[138:139], v233 offset:0x2400
	ds_read_b64_tr_b16 v[140:141], v233 offset:0x2c00
	v_exp_f32_e32 v122, v122
	v_exp_f32_e32 v123, v123
	v_add_f32_e32 v209, v118, v209
	v_add_f32_e32 v209, v119, v209
	v_fma_f32 v246, v74, s12, v160
	v_fma_f32 v247, v75, s12, v160
	v_fma_f32 v76, v76, s12, v160
	v_fma_f32 v77, v77, s12, v160
	v_mfma_f32_32x32x16_bf16 v[16:31], v[166:169], v[126:129], v[16:31]
	ds_read_b64_tr_b16 v[64:65], v233 offset:0x3400
	ds_read_b64_tr_b16 v[66:67], v233 offset:0x3c00
	v_exp_f32_e32 v124, v124
	v_exp_f32_e32 v125, v125
	v_add_f32_e32 v209, v120, v209
	v_add_f32_e32 v209, v121, v209
	v_add_f32_e32 v209, v122, v209
	v_add_f32_e32 v209, v123, v209
	v_fma_f32 v78, v78, s12, v160
	v_fma_f32 v79, v79, s12, v160
	s_waitcnt lgkmcnt(6)
	v_mfma_f32_32x32x16_bf16 v[32:47], v[114:117], v[146:149], v[32:47]
	v_exp_f32_e32 v244, v244
	v_exp_f32_e32 v245, v245
	v_add_f32_e32 v209, v124, v209
	v_add_f32_e32 v209, v125, v209
	s_waitcnt lgkmcnt(4)
	v_mfma_f32_32x32x16_bf16 v[32:47], v[130:133], v[142:145], v[32:47]
	ds_read_b64_tr_b16 v[142:143], v216 offset:0x600
	ds_read_b64_tr_b16 v[144:145], v216 offset:0xe00
	ds_read_b64_tr_b16 v[126:127], v216 offset:0x1600
	ds_read_b64_tr_b16 v[128:129], v216 offset:0x1e00
	v_exp_f32_e32 v246, v246
	v_exp_f32_e32 v247, v247
	s_waitcnt lgkmcnt(6)
	v_mfma_f32_32x32x16_bf16 v[32:47], v[162:165], v[138:141], v[32:47]
	ds_read_b64_tr_b16 v[134:135], v233 offset:0x2600
	ds_read_b64_tr_b16 v[136:137], v233 offset:0x2e00
	v_exp_f32_e32 v76, v76
	v_exp_f32_e32 v77, v77
	v_add_f32_e32 v209, v244, v209
	v_add_f32_e32 v209, v245, v209
	s_waitcnt lgkmcnt(6)
	v_mfma_f32_32x32x16_bf16 v[32:47], v[166:169], v[64:67], v[32:47]
	ds_read_b64_tr_b16 v[68:69], v233 offset:0x3600
	ds_read_b64_tr_b16 v[70:71], v233 offset:0x3e00
	v_exp_f32_e32 v78, v78
	v_exp_f32_e32 v79, v79
	v_add_f32_e32 v209, v246, v209
	v_add_f32_e32 v209, v247, v209
	s_waitcnt lgkmcnt(6)
	v_mfma_f32_32x32x16_bf16 v[48:63], v[114:117], v[142:145], v[48:63]
	v_add_u32_e32 v64, s19, v211
	v_add_f32_e32 v209, v76, v209
	v_add_f32_e32 v209, v77, v209
	v_cvt_pk_bf16_f32 v114, v118, v119
	v_cvt_pk_bf16_f32 v115, v120, v121
	v_cvt_pk_bf16_f32 v116, v122, v123
	v_cvt_pk_bf16_f32 v117, v124, v125
	s_waitcnt lgkmcnt(4)
	v_mfma_f32_32x32x16_bf16 v[48:63], v[130:133], v[126:129], v[48:63]
	v_add_f32_e32 v209, v78, v209
	v_add_f32_e32 v209, v79, v209
	v_permlane32_swap_b32_e32 v114, v116
	v_permlane32_swap_b32_e32 v115, v117
	v_cvt_pk_bf16_f32 v130, v244, v245
	v_cvt_pk_bf16_f32 v131, v246, v247
	v_cvt_pk_bf16_f32 v132, v76, v77
	v_cvt_pk_bf16_f32 v133, v78, v79
	ds_write_b128 v64, v[114:117]
	s_waitcnt lgkmcnt(3)
	v_mfma_f32_32x32x16_bf16 v[48:63], v[162:165], v[134:137], v[48:63]
	v_permlane32_swap_b32_e32 v130, v132
	v_permlane32_swap_b32_e32 v131, v133
	ds_write_b128 v64, v[130:133] offset:16
	s_add_i32 s55, s55, 1
	s_add_i32 s18, s18, 64
	s_add_i32 s54, s54, 0x8000
	s_add_i32 s100, s18, -1
	s_cmp_ge_i32 s100, s33
	s_cselect_b32 s100, 1, 0
	s_sub_i32 s101, s18, 64
	s_cmp_le_i32 s101, s35
	s_cselect_b32 s101, 1, 0
	s_and_b32 s100, s100, s101
	s_cmp_eq_u32 s83, s55
	s_waitcnt vmcnt(0) lgkmcnt(0)
	s_barrier
	v_mfma_f32_32x32x16_bf16 v[48:63], v[166:169], v[68:71], v[48:63]
	s_cbranch_scc1 .LBB0_265
	s_cmp_lg_u32 s100, 0
	s_cbranch_scc1 .Lgen0
	s_branch .Lfast0

; #define SBAR() __builtin_amdgcn_sched_barrier(0)
; #define KDMA(k0, b) do { const char* g_ = (const char*)(Kh + (long)(k0) * DM); char* l_ = K_lds + (b) * 16384 + wu * 1024; \
;     DMA16(g_ + koff[0], l_); DMA16(g_ + koff[1], l_ + 8192); } while (0)
; #define VDMA(k0, b) do { const char* g_ = (const char*)(Vh + (long)(k0) * DM); char* l_ = V_lds + (b) * 32768 + wu * 1024; \
;     DMA16(g_ + voff[0], l_); DMA16(g_ + voff[1], l_ + 8192); DMA16(g_ + voff[0] + 256, l_ + 16384); DMA16(g_ + voff[1] + 256, l_ + 16384 + 8192); } while (0)
; #define LWAIT() do { asm volatile("s_waitcnt lgkmcnt(0)" ::: "memory"); SBAR(); } while (0)
; #define VMMP(D0, X) do { if (!(PROBE & 8)) VMM(D0, X); } while (0)
; #define SMXP(c) do { if (!(PROBE & 2)) { if (more) SMX_CH(c); } } while (0)
; template <int PROBE, int MODE>
; DI void dattn_body(const u16* __restrict__ Qb, const u16* __restrict__ Kh, const u16* __restrict__ Vh, u16* __restrict__ Ob, const u16* __restrict__ O1, float lam, const float* __restrict__ subg, int seq, int q0, float kmax2, char* lds) {
;     ...
;   for (int j = 0; j < NT; ++j) {
;     const bool more = j + 1 < NT;
;     if (!(PROBE & 1)) {
;       if (j + 2 < NT) KDMA((j + 2) * KVBLK, j & 1);
;       if (more) VDMA((j + 1) * KVBLK, (j + 1) & 1);
;     }
;     bf16x8 kf[8];
;     if (more) { const char* Ks_ = K_lds + ((j + 1) & 1) * 16384;
; #pragma unroll
;       for (int d0 = 0; d0 < 8; ++d0) kf[d0] = *reinterpret_cast<const bf16x8*>(Ks_ + KSWZ(32 * kh + r32, (d0 * 16 + hi * 8) * 2)); }
;     const bf16x8 pb0 = *(const bf16x8*)(pr + (j & 1) * 16384), pb1 = *(const bf16x8*)(pr + (j & 1) * 16384 + 16);
;     const int vb = vb0 + (j & 1) * 32768;
;     s16x4 va0, va1, va2, va3, va4, va5, va6, va7, vc0, vc1, vc2, vc3, vc4, vc5, vc6, vc7;
;     VRD(0, va);
;     if (more) { asm volatile("s_waitcnt lgkmcnt(10)" ::: "memory"); SBAR();
;       if (!(PROBE & 4)) { S = f32x16{};
; #pragma unroll
;       for (int d0 = 0; d0 < 8; ++d0) S = __builtin_amdgcn_mfma_f32_32x32x16_bf16(kf[d0], qr[d0], S, 0, 0, 0); }
;       SBAR(); }
;     const bf16x8 A0 = kh ? pb0 : po0, A1 = kh ? pb1 : po1, A2 = kh ? po0 : pb0, A3 = kh ? po1 : pb1;
;     SMX_SETUP(j + 1)
;     ...
;     LWAIT(); VRD(1, vc); VMMP(0, va); SMXP(0);
;     LWAIT(); VRD(2, va); VMMP(1, vc); SMXP(1);
;     LWAIT(); VRD(3, vc); VMMP(2, va); SMXP(2);
;     LWAIT(); VMMP(3, vc); SMXP(3);
.Lfast1:
	s_sub_i32 s72, s0, 64
	s_and_b32 s101, s24, 0x4000
	s_addk_i32 s24, 0x4000
	s_and_b32 s1, s24, 0x4000
	s_and_b32 s4, s40, 1
	v_lshl_add_u32 v71, s4, 14, v209
	s_bfe_u32 s100, s39, 0x1000a
	s_lshl_b32 s100, s100, 13
	s_lshl_b32 s4, s4, 15
	s_sub_i32 s18, s4, s100
	s_add_i32 s4, s4, s100
	v_add_u32_e32 v215, s4, v211
	v_add_u32_e32 v233, s18, v211
	v_add_u32_e32 v68, s1, v212
	v_add_u32_e32 v64, v68, v196
	v_add_u32_e32 v69, v68, v198
	ds_read_b64_tr_b16 v[234:235], v215 offset:0
	ds_read_b64_tr_b16 v[236:237], v215 offset:0x800
	ds_read_b128 v[64:67], v64
	ds_read_b128 v[118:121], v69
	ds_read_b128 v[162:165], v71
	ds_read_b128 v[166:169], v71 offset:16
	v_add_u32_e32 v69, v68, v199
	v_add_u32_e32 v70, v68, v200
	ds_read_b128 v[122:125], v69
	ds_read_b128 v[126:129], v70
	ds_read_b64_tr_b16 v[238:239], v215 offset:0x1000
	ds_read_b64_tr_b16 v[240:241], v215 offset:0x1800
	v_add_u32_e32 v69, v68, v201
	v_add_u32_e32 v70, v68, v202
	ds_read_b128 v[134:137], v69
	ds_read_b128 v[138:141], v70
	v_add_u32_e32 v142, v68, v203
	v_add_u32_e32 v146, v68, v204
	s_cmp_gt_i32 s72, s87
	s_cselect_b32 s100, s21, s20
	v_sub_f32_e32 v160, s100, v158
	s_lshl_b32 s4, s72, 12
	s_add_u32 s4, s16, s4
	s_addc_u32 s5, s17, 0
	s_add_u32 s18, s4, 0x100
	s_addc_u32 s19, s5, 0
	s_and_b32 s100, s25, 0x8000
	s_add_i32 s100, s39, s100
	s_mov_b32 m0, s100
	s_waitcnt lgkmcnt(10)
	v_mfma_f32_32x32x16_bf16 v[0:15], v[114:117], v[234:237], v[0:15]
	global_load_lds_dwordx4 v152, s[4:5]
	ds_read_b64_tr_b16 v[242:243], v233 offset:0x2000
	ds_read_b64_tr_b16 v[244:245], v233 offset:0x2800
	s_add_i32 m0, s100, 0x2000
	s_waitcnt lgkmcnt(11)
	v_mfma_f32_32x32x16_bf16 v[64:79], v[64:67], v[82:85], 0
	global_load_lds_dwordx4 v156, s[4:5]
	ds_read_b128 v[142:145], v142
	ds_read_b128 v[146:149], v146
	s_add_i32 m0, s100, 0x4000
	s_waitcnt lgkmcnt(12)
	v_mfma_f32_32x32x16_bf16 v[64:79], v[118:121], v[86:89], v[64:79]
	global_load_lds_dwordx4 v152, s[18:19]
	ds_read_b64_tr_b16 v[246:247], v233 offset:0x3000
	ds_read_b64_tr_b16 v[248:249], v233 offset:0x3800
	s_add_i32 m0, s100, 0x6000
	s_waitcnt lgkmcnt(11)
	v_mfma_f32_32x32x16_bf16 v[64:79], v[122:125], v[90:93], v[64:79]
	global_load_lds_dwordx4 v156, s[18:19]
	s_waitcnt lgkmcnt(10)
	v_mfma_f32_32x32x16_bf16 v[64:79], v[126:129], v[94:97], v[64:79]
	ds_read_b64_tr_b16 v[126:127], v233 offset:0x3200
	ds_read_b64_tr_b16 v[128:129], v233 offset:0x3a00
	s_waitcnt lgkmcnt(10)
	v_mfma_f32_32x32x16_bf16 v[0:15], v[130:133], v[238:241], v[0:15]
	s_add_i32 s4, s40, 2
	s_cmp_ge_u32 s4, s11
	s_cbranch_scc1 .Lfast1_k_done
	s_lshl_b32 s4, s0, 12
	s_add_u32 s4, s14, s4
	s_addc_u32 s5, s15, 0
	s_add_u32 s4, s4, 0x100
	s_addc_u32 s5, s5, 0
	s_add_i32 s100, s38, s101
	s_mov_b32 m0, s100
	s_nop 0
	global_load_lds_dwordx4 v176, s[4:5]
	s_add_i32 m0, s100, 0x2000
	s_nop 0
	global_load_lds_dwordx4 v154, s[4:5]
; #define DMAWAIT() asm volatile("s_waitcnt vmcnt(0)" ::: "memory")
; #define SMX_FIN(pbuf) do { _Pragma("unroll") for (int r = 0; r < 16; ++r) l_reg += S[r]; \
;     PK4S(0, po0); PK4S(8, po1); \
;     *(bf16x8*)(pw + (pbuf) * 16384) = po0; *(bf16x8*)(pw + (pbuf) * 16384 + 16) = po1; } while (0)
; #define VRD(D0, X) do { X##0 = tr_read<v_rd_off(D0, 0, 0)>(vb); X##1 = tr_read<v_rd_off(D0, 0, 1)>(vb); X##2 = tr_read<v_rd_off(D0, 1, 0)>(vb); X##3 = tr_read<v_rd_off(D0, 1, 1)>(vb); \
;     X##4 = tr_read<v_rd_off(D0, 2, 0)>(vb); X##5 = tr_read<v_rd_off(D0, 2, 1)>(vb); X##6 = tr_read<v_rd_off(D0, 3, 0)>(vb); X##7 = tr_read<v_rd_off(D0, 3, 1)>(vb); } while (0)
; #define LWAIT() do { asm volatile("s_waitcnt lgkmcnt(0)" ::: "memory"); SBAR(); } while (0)
; #define VMMP(D0, X) do { if (!(PROBE & 8)) VMM(D0, X); } while (0)
; #define SMXP(c) do { if (!(PROBE & 2)) { if (more) SMX_CH(c); } } while (0)
; template <int PROBE, int MODE>
; DI void dattn_body(const u16* __restrict__ Qb, const u16* __restrict__ Kh, const u16* __restrict__ Vh, u16* __restrict__ Ob, const u16* __restrict__ O1, float lam, const float* __restrict__ subg, int seq, int q0, float kmax2, char* lds) {
;     ...
;     LWAIT(); VRD(1, vc); VMMP(0, va); SMXP(0);
;     LWAIT(); VRD(2, va); VMMP(1, vc); SMXP(1);
;     LWAIT(); VRD(3, vc); VMMP(2, va); SMXP(2);
;     LWAIT(); VMMP(3, vc); SMXP(3);
;     if (!(PROBE & 2)) { if (more) SMX_FIN((j + 1) & 1); }
;     DMAWAIT();
;     __syncthreads();
.Lfast1_k_done:
	s_waitcnt lgkmcnt(9)
	v_mfma_f32_32x32x16_bf16 v[64:79], v[134:137], v[98:101], v[64:79]
	ds_read_b64_tr_b16 v[134:135], v233 offset:0x2200
	ds_read_b64_tr_b16 v[136:137], v233 offset:0x2a00
	s_waitcnt lgkmcnt(10)
	v_mfma_f32_32x32x16_bf16 v[64:79], v[138:141], v[102:105], v[64:79]
	ds_read_b64_tr_b16 v[138:139], v215 offset:0x200
	ds_read_b64_tr_b16 v[140:141], v215 offset:0xa00
	s_waitcnt lgkmcnt(10)
	v_mfma_f32_32x32x16_bf16 v[0:15], v[162:165], v[242:245], v[0:15]
	s_waitcnt lgkmcnt(9)
	v_mfma_f32_32x32x16_bf16 v[64:79], v[142:145], v[106:109], v[64:79]
	ds_read_b64_tr_b16 v[142:143], v215 offset:0x1200
	ds_read_b64_tr_b16 v[144:145], v215 offset:0x1a00
	s_waitcnt lgkmcnt(10)
	v_mfma_f32_32x32x16_bf16 v[64:79], v[146:149], v[110:113], v[64:79]
	s_waitcnt lgkmcnt(8)
	v_mfma_f32_32x32x16_bf16 v[0:15], v[166:169], v[246:249], v[0:15]
	s_waitcnt lgkmcnt(2)
	v_mfma_f32_32x32x16_bf16 v[16:31], v[114:117], v[138:141], v[16:31]
	ds_read_b64_tr_b16 v[146:147], v215 offset:0x400
	ds_read_b64_tr_b16 v[148:149], v215 offset:0xc00
	s_nop 7
	s_nop 0
	v_fma_f32 v118, v64, s12, v160
	v_fma_f32 v119, v65, s12, v160
	v_fma_f32 v120, v66, s12, v160
	v_fma_f32 v121, v67, s12, v160
	v_fma_f32 v122, v68, s12, v160
	v_fma_f32 v123, v69, s12, v160
	s_waitcnt lgkmcnt(2)
	v_mfma_f32_32x32x16_bf16 v[16:31], v[130:133], v[142:145], v[16:31]
	ds_read_b64_tr_b16 v[142:143], v215 offset:0x1400
	ds_read_b64_tr_b16 v[144:145], v215 offset:0x1c00
	v_fma_f32 v124, v70, s12, v160
	v_fma_f32 v125, v71, s12, v160
	v_exp_f32_e32 v118, v118
	v_exp_f32_e32 v119, v119
	v_exp_f32_e32 v120, v120
	v_exp_f32_e32 v121, v121
	v_fma_f32 v244, v72, s12, v160
	v_fma_f32 v245, v73, s12, v160
	v_mfma_f32_32x32x16_bf16 v[16:31], v[162:165], v[134:137], v[16:31]
	ds_read_b64_tr_b16 v[138:139], v233 offset:0x2400
	ds_read_b64_tr_b16 v[140:141], v233 offset:0x2c00
	v_exp_f32_e32 v122, v122
	v_exp_f32_e32 v123, v123
	v_add_f32_e32 v208, v118, v208
	v_add_f32_e32 v208, v119, v208
	v_fma_f32 v246, v74, s12, v160
	v_fma_f32 v247, v75, s12, v160
	v_fma_f32 v76, v76, s12, v160
	v_fma_f32 v77, v77, s12, v160
	v_mfma_f32_32x32x16_bf16 v[16:31], v[166:169], v[126:129], v[16:31]
	ds_read_b64_tr_b16 v[64:65], v233 offset:0x3400
	ds_read_b64_tr_b16 v[66:67], v233 offset:0x3c00
	v_exp_f32_e32 v124, v124
	v_exp_f32_e32 v125, v125
	v_add_f32_e32 v208, v120, v208
	v_add_f32_e32 v208, v121, v208
	v_add_f32_e32 v208, v122, v208
	v_add_f32_e32 v208, v123, v208
	v_fma_f32 v78, v78, s12, v160
	v_fma_f32 v79, v79, s12, v160
	s_waitcnt lgkmcnt(6)
	v_mfma_f32_32x32x16_bf16 v[32:47], v[114:117], v[146:149], v[32:47]
	v_exp_f32_e32 v244, v244
	v_exp_f32_e32 v245, v245
	v_add_f32_e32 v208, v124, v208
	v_add_f32_e32 v208, v125, v208
	s_waitcnt lgkmcnt(4)
	v_mfma_f32_32x32x16_bf16 v[32:47], v[130:133], v[142:145], v[32:47]
	ds_read_b64_tr_b16 v[142:143], v215 offset:0x600
	ds_read_b64_tr_b16 v[144:145], v215 offset:0xe00
	ds_read_b64_tr_b16 v[126:127], v215 offset:0x1600
	ds_read_b64_tr_b16 v[128:129], v215 offset:0x1e00
	v_exp_f32_e32 v246, v246
	v_exp_f32_e32 v247, v247
	s_waitcnt lgkmcnt(6)
	v_mfma_f32_32x32x16_bf16 v[32:47], v[162:165], v[138:141], v[32:47]
	ds_read_b64_tr_b16 v[134:135], v233 offset:0x2600
	ds_read_b64_tr_b16 v[136:137], v233 offset:0x2e00
	v_exp_f32_e32 v76, v76
	v_exp_f32_e32 v77, v77
	v_add_f32_e32 v208, v244, v208
	v_add_f32_e32 v208, v245, v208
	s_waitcnt lgkmcnt(6)
	v_mfma_f32_32x32x16_bf16 v[32:47], v[166:169], v[64:67], v[32:47]
	ds_read_b64_tr_b16 v[68:69], v233 offset:0x3600
	ds_read_b64_tr_b16 v[70:71], v233 offset:0x3e00
	v_exp_f32_e32 v78, v78
	v_exp_f32_e32 v79, v79
	v_add_f32_e32 v208, v246, v208
	v_add_f32_e32 v208, v247, v208
	s_waitcnt lgkmcnt(6)
	v_mfma_f32_32x32x16_bf16 v[48:63], v[114:117], v[142:145], v[48:63]
	v_add_u32_e32 v64, s1, v210
	v_add_f32_e32 v208, v76, v208
	v_add_f32_e32 v208, v77, v208
	v_cvt_pk_bf16_f32 v114, v118, v119
	v_cvt_pk_bf16_f32 v115, v120, v121
	v_cvt_pk_bf16_f32 v116, v122, v123
	v_cvt_pk_bf16_f32 v117, v124, v125
	s_waitcnt lgkmcnt(4)
	v_mfma_f32_32x32x16_bf16 v[48:63], v[130:133], v[126:129], v[48:63]
	v_add_f32_e32 v208, v78, v208
	v_add_f32_e32 v208, v79, v208
	v_permlane32_swap_b32_e32 v114, v116
	v_permlane32_swap_b32_e32 v115, v117
	v_cvt_pk_bf16_f32 v130, v244, v245
	v_cvt_pk_bf16_f32 v131, v246, v247
	v_cvt_pk_bf16_f32 v132, v76, v77
	v_cvt_pk_bf16_f32 v133, v78, v79
	ds_write_b128 v64, v[114:117]
	s_waitcnt lgkmcnt(3)
	v_mfma_f32_32x32x16_bf16 v[48:63], v[162:165], v[134:137], v[48:63]
	v_permlane32_swap_b32_e32 v130, v132
	v_permlane32_swap_b32_e32 v131, v133
	ds_write_b128 v64, v[130:133] offset:16
	s_add_i32 s40, s40, 1
	s_add_i32 s0, s0, 64
	s_add_i32 s25, s25, 0x8000
	s_add_i32 s100, s0, -1
	s_cmp_ge_i32 s100, s33
	s_cselect_b32 s100, 1, 0
	s_sub_i32 s101, s0, 64
	s_cmp_le_i32 s101, s35
	s_cselect_b32 s101, 1, 0
	s_and_b32 s100, s100, s101
	s_cmp_eq_u32 s83, s40
	s_waitcnt vmcnt(0) lgkmcnt(0)
	s_barrier
	v_mfma_f32_32x32x16_bf16 v[48:63], v[166:169], v[68:71], v[48:63]
	s_cbranch_scc1 .LBB0_303
	s_cmp_lg_u32 s100, 0
	s_cbranch_scc1 .Lgen1
	s_branch .Lfast1
